# prep silu(c) staging: 20 loads in flight; post1 V^T tile load: 10 loads in flight (both were one exposed load latency per iteration)
# speedup vs baseline: 1.0058x; 1.0042x over previous
.LBB0_663:
	s_lshl_b32 s8, s0, 6
	s_waitcnt vmcnt(0) lgkmcnt(0)
	s_barrier
	s_and_saveexec_b64 s[10:11], vcc
	s_movk_i32 s9, 0x1c00
	s_cbranch_execz .LBB0_666
	s_mov_b64 s[12:13], 0
	v_mov_b32_e32 v7, v6
	v_mov_b32_e32 v8, v4
	v_mov_b32_e32 v2, v3
	s_mov_b32 s1, 0x66666667
	v_mul_hi_i32 v9, v2, s1
	v_lshrrev_b32_e32 v10, 31, v9
	v_ashrrev_i32_e32 v9, 5, v9
	v_add_u32_e32 v9, v9, v10
	s_movk_i32 s1, 0xffb0
	v_mad_u64_u32 v[10:11], s[6:7], v9, s1, v[2:3]
	v_cmp_gt_i32_e64 s[6:7], 64, v10
	v_mov_b32_e32 v10, 0x8c0
	v_mov_b32_e32 v11, 0x400
	s_movk_i32 s1, 0x280
	v_cndmask_b32_e64 v10, v10, v11, s[6:7]
	v_mul_lo_u32 v11, v9, s1
	v_sub_u32_e32 v10, v10, v11
	v_add_u32_e32 v10, v7, v10
	v_add_u32_e32 v11, s8, v9
	v_mov_b64_e32 v[12:13], s[90:91]
	v_mad_i64_i32 v[12:13], s[6:7], v11, s9, v[12:13]
	v_ashrrev_i32_e32 v11, 31, v10
	v_lshl_add_u64 v[10:11], v[10:11], 1, v[12:13]
	global_load_dwordx4 v[100:103], v[10:11], off
	v_lshl_add_u32 v140, v9, 4, v8
	v_add_u32_e32 v8, 0x2000, v8
	v_add_u32_e32 v7, 0x1000, v7
	v_add_u32_e32 v2, 0x200, v2
	s_mov_b32 s1, 0x66666667
	v_mul_hi_i32 v9, v2, s1
	v_lshrrev_b32_e32 v10, 31, v9
	v_ashrrev_i32_e32 v9, 5, v9
	v_add_u32_e32 v9, v9, v10
	s_movk_i32 s1, 0xffb0
	v_mad_u64_u32 v[10:11], s[6:7], v9, s1, v[2:3]
	v_cmp_gt_i32_e64 s[6:7], 64, v10
	v_mov_b32_e32 v10, 0x8c0
	v_mov_b32_e32 v11, 0x400
	s_movk_i32 s1, 0x280
	v_cndmask_b32_e64 v10, v10, v11, s[6:7]
	v_mul_lo_u32 v11, v9, s1
	v_sub_u32_e32 v10, v10, v11
	v_add_u32_e32 v10, v7, v10
	v_add_u32_e32 v11, s8, v9
	v_mov_b64_e32 v[12:13], s[90:91]
	v_mad_i64_i32 v[12:13], s[6:7], v11, s9, v[12:13]
	v_ashrrev_i32_e32 v11, 31, v10
	v_lshl_add_u64 v[10:11], v[10:11], 1, v[12:13]
	global_load_dwordx4 v[104:107], v[10:11], off
	v_lshl_add_u32 v141, v9, 4, v8
	v_add_u32_e32 v8, 0x2000, v8
	v_add_u32_e32 v7, 0x1000, v7
	v_add_u32_e32 v2, 0x200, v2
	s_mov_b32 s1, 0x66666667
	v_mul_hi_i32 v9, v2, s1
	v_lshrrev_b32_e32 v10, 31, v9
	v_ashrrev_i32_e32 v9, 5, v9
	v_add_u32_e32 v9, v9, v10
	s_movk_i32 s1, 0xffb0
	v_mad_u64_u32 v[10:11], s[6:7], v9, s1, v[2:3]
	v_cmp_gt_i32_e64 s[6:7], 64, v10
	v_mov_b32_e32 v10, 0x8c0
	v_mov_b32_e32 v11, 0x400
	s_movk_i32 s1, 0x280
	v_cndmask_b32_e64 v10, v10, v11, s[6:7]
	v_mul_lo_u32 v11, v9, s1
	v_sub_u32_e32 v10, v10, v11
	v_add_u32_e32 v10, v7, v10
	v_add_u32_e32 v11, s8, v9
	v_mov_b64_e32 v[12:13], s[90:91]
	v_mad_i64_i32 v[12:13], s[6:7], v11, s9, v[12:13]
	v_ashrrev_i32_e32 v11, 31, v10
	v_lshl_add_u64 v[10:11], v[10:11], 1, v[12:13]
	global_load_dwordx4 v[108:111], v[10:11], off
	v_lshl_add_u32 v142, v9, 4, v8
	v_add_u32_e32 v8, 0x2000, v8
	v_add_u32_e32 v7, 0x1000, v7
	v_add_u32_e32 v2, 0x200, v2
	s_mov_b32 s1, 0x66666667
	v_mul_hi_i32 v9, v2, s1
	v_lshrrev_b32_e32 v10, 31, v9
	v_ashrrev_i32_e32 v9, 5, v9
	v_add_u32_e32 v9, v9, v10
	s_movk_i32 s1, 0xffb0
	v_mad_u64_u32 v[10:11], s[6:7], v9, s1, v[2:3]
	v_cmp_gt_i32_e64 s[6:7], 64, v10
	v_mov_b32_e32 v10, 0x8c0
	v_mov_b32_e32 v11, 0x400
	s_movk_i32 s1, 0x280
	v_cndmask_b32_e64 v10, v10, v11, s[6:7]
	v_mul_lo_u32 v11, v9, s1
	v_sub_u32_e32 v10, v10, v11
	v_add_u32_e32 v10, v7, v10
	v_add_u32_e32 v11, s8, v9
	v_mov_b64_e32 v[12:13], s[90:91]
	v_mad_i64_i32 v[12:13], s[6:7], v11, s9, v[12:13]
	v_ashrrev_i32_e32 v11, 31, v10
	v_lshl_add_u64 v[10:11], v[10:11], 1, v[12:13]
	global_load_dwordx4 v[112:115], v[10:11], off
	v_lshl_add_u32 v143, v9, 4, v8
	v_add_u32_e32 v8, 0x2000, v8
	v_add_u32_e32 v7, 0x1000, v7
	v_add_u32_e32 v2, 0x200, v2
	s_mov_b32 s1, 0x66666667
	v_mul_hi_i32 v9, v2, s1
	v_lshrrev_b32_e32 v10, 31, v9
	v_ashrrev_i32_e32 v9, 5, v9
	v_add_u32_e32 v9, v9, v10
	s_movk_i32 s1, 0xffb0
	v_mad_u64_u32 v[10:11], s[6:7], v9, s1, v[2:3]
	v_cmp_gt_i32_e64 s[6:7], 64, v10
	v_mov_b32_e32 v10, 0x8c0
	v_mov_b32_e32 v11, 0x400
	s_movk_i32 s1, 0x280
	v_cndmask_b32_e64 v10, v10, v11, s[6:7]
	v_mul_lo_u32 v11, v9, s1
	v_sub_u32_e32 v10, v10, v11
	v_add_u32_e32 v10, v7, v10
	v_add_u32_e32 v11, s8, v9
	v_mov_b64_e32 v[12:13], s[90:91]
	v_mad_i64_i32 v[12:13], s[6:7], v11, s9, v[12:13]
	v_ashrrev_i32_e32 v11, 31, v10
	v_lshl_add_u64 v[10:11], v[10:11], 1, v[12:13]
	global_load_dwordx4 v[116:119], v[10:11], off
	v_lshl_add_u32 v144, v9, 4, v8
	v_add_u32_e32 v8, 0x2000, v8
	v_add_u32_e32 v7, 0x1000, v7
	v_add_u32_e32 v2, 0x200, v2
	s_mov_b32 s1, 0x66666667
	v_mul_hi_i32 v9, v2, s1
	v_lshrrev_b32_e32 v10, 31, v9
	v_ashrrev_i32_e32 v9, 5, v9
	v_add_u32_e32 v9, v9, v10
	s_movk_i32 s1, 0xffb0
	v_mad_u64_u32 v[10:11], s[6:7], v9, s1, v[2:3]
	v_cmp_gt_i32_e64 s[6:7], 64, v10
	v_mov_b32_e32 v10, 0x8c0
	v_mov_b32_e32 v11, 0x400
	s_movk_i32 s1, 0x280
	v_cndmask_b32_e64 v10, v10, v11, s[6:7]
	v_mul_lo_u32 v11, v9, s1
	v_sub_u32_e32 v10, v10, v11
	v_add_u32_e32 v10, v7, v10
	v_add_u32_e32 v11, s8, v9
	v_mov_b64_e32 v[12:13], s[90:91]
	v_mad_i64_i32 v[12:13], s[6:7], v11, s9, v[12:13]
	v_ashrrev_i32_e32 v11, 31, v10
	v_lshl_add_u64 v[10:11], v[10:11], 1, v[12:13]
	global_load_dwordx4 v[120:123], v[10:11], off
	v_lshl_add_u32 v145, v9, 4, v8
	v_add_u32_e32 v8, 0x2000, v8
	v_add_u32_e32 v7, 0x1000, v7
	v_add_u32_e32 v2, 0x200, v2
	s_mov_b32 s1, 0x66666667
	v_mul_hi_i32 v9, v2, s1
	v_lshrrev_b32_e32 v10, 31, v9
	v_ashrrev_i32_e32 v9, 5, v9
	v_add_u32_e32 v9, v9, v10
	s_movk_i32 s1, 0xffb0
	v_mad_u64_u32 v[10:11], s[6:7], v9, s1, v[2:3]
	v_cmp_gt_i32_e64 s[6:7], 64, v10
	v_mov_b32_e32 v10, 0x8c0
	v_mov_b32_e32 v11, 0x400
	s_movk_i32 s1, 0x280
	v_cndmask_b32_e64 v10, v10, v11, s[6:7]
	v_mul_lo_u32 v11, v9, s1
	v_sub_u32_e32 v10, v10, v11
	v_add_u32_e32 v10, v7, v10
	v_add_u32_e32 v11, s8, v9
	v_mov_b64_e32 v[12:13], s[90:91]
	v_mad_i64_i32 v[12:13], s[6:7], v11, s9, v[12:13]
	v_ashrrev_i32_e32 v11, 31, v10
	v_lshl_add_u64 v[10:11], v[10:11], 1, v[12:13]
	global_load_dwordx4 v[124:127], v[10:11], off
	v_lshl_add_u32 v146, v9, 4, v8
	v_add_u32_e32 v8, 0x2000, v8
	v_add_u32_e32 v7, 0x1000, v7
	v_add_u32_e32 v2, 0x200, v2
	s_mov_b32 s1, 0x66666667
	v_mul_hi_i32 v9, v2, s1
	v_lshrrev_b32_e32 v10, 31, v9
	v_ashrrev_i32_e32 v9, 5, v9
	v_add_u32_e32 v9, v9, v10
	s_movk_i32 s1, 0xffb0
	v_mad_u64_u32 v[10:11], s[6:7], v9, s1, v[2:3]
	v_cmp_gt_i32_e64 s[6:7], 64, v10
	v_mov_b32_e32 v10, 0x8c0
	v_mov_b32_e32 v11, 0x400
	s_movk_i32 s1, 0x280
	v_cndmask_b32_e64 v10, v10, v11, s[6:7]
	v_mul_lo_u32 v11, v9, s1
	v_sub_u32_e32 v10, v10, v11
	v_add_u32_e32 v10, v7, v10
	v_add_u32_e32 v11, s8, v9
	v_mov_b64_e32 v[12:13], s[90:91]
	v_mad_i64_i32 v[12:13], s[6:7], v11, s9, v[12:13]
	v_ashrrev_i32_e32 v11, 31, v10
	v_lshl_add_u64 v[10:11], v[10:11], 1, v[12:13]
	global_load_dwordx4 v[128:131], v[10:11], off
	v_lshl_add_u32 v147, v9, 4, v8
	v_add_u32_e32 v8, 0x2000, v8
	v_add_u32_e32 v7, 0x1000, v7
	v_add_u32_e32 v2, 0x200, v2
	s_mov_b32 s1, 0x66666667
	v_mul_hi_i32 v9, v2, s1
	v_lshrrev_b32_e32 v10, 31, v9
	v_ashrrev_i32_e32 v9, 5, v9
	v_add_u32_e32 v9, v9, v10
	s_movk_i32 s1, 0xffb0
	v_mad_u64_u32 v[10:11], s[6:7], v9, s1, v[2:3]
	v_cmp_gt_i32_e64 s[6:7], 64, v10
	v_mov_b32_e32 v10, 0x8c0
	v_mov_b32_e32 v11, 0x400
	s_movk_i32 s1, 0x280
	v_cndmask_b32_e64 v10, v10, v11, s[6:7]
	v_mul_lo_u32 v11, v9, s1
	v_sub_u32_e32 v10, v10, v11
	v_add_u32_e32 v10, v7, v10
	v_add_u32_e32 v11, s8, v9
	v_mov_b64_e32 v[12:13], s[90:91]
	v_mad_i64_i32 v[12:13], s[6:7], v11, s9, v[12:13]
	v_ashrrev_i32_e32 v11, 31, v10
	v_lshl_add_u64 v[10:11], v[10:11], 1, v[12:13]
	global_load_dwordx4 v[132:135], v[10:11], off
	v_lshl_add_u32 v148, v9, 4, v8
	v_add_u32_e32 v8, 0x2000, v8
	v_add_u32_e32 v7, 0x1000, v7
	v_add_u32_e32 v2, 0x200, v2
	s_mov_b32 s1, 0x66666667
	v_mul_hi_i32 v9, v2, s1
	v_lshrrev_b32_e32 v10, 31, v9
	v_ashrrev_i32_e32 v9, 5, v9
	v_add_u32_e32 v9, v9, v10
	s_movk_i32 s1, 0xffb0
	v_mad_u64_u32 v[10:11], s[6:7], v9, s1, v[2:3]
	v_cmp_gt_i32_e64 s[6:7], 64, v10
	v_mov_b32_e32 v10, 0x8c0
	v_mov_b32_e32 v11, 0x400
	s_movk_i32 s1, 0x280
	v_cndmask_b32_e64 v10, v10, v11, s[6:7]
	v_mul_lo_u32 v11, v9, s1
	v_sub_u32_e32 v10, v10, v11
	v_add_u32_e32 v10, v7, v10
	v_add_u32_e32 v11, s8, v9
	v_mov_b64_e32 v[12:13], s[90:91]
	v_mad_i64_i32 v[12:13], s[6:7], v11, s9, v[12:13]
	v_ashrrev_i32_e32 v11, 31, v10
	v_lshl_add_u64 v[10:11], v[10:11], 1, v[12:13]
	global_load_dwordx4 v[136:139], v[10:11], off
	v_lshl_add_u32 v149, v9, 4, v8
	v_add_u32_e32 v8, 0x2000, v8
	v_add_u32_e32 v7, 0x1000, v7
	v_add_u32_e32 v2, 0x200, v2
	s_waitcnt vmcnt(9)
	ds_write_b128 v140, v[100:103]
	s_waitcnt vmcnt(8)
	ds_write_b128 v141, v[104:107]
	s_waitcnt vmcnt(7)
	ds_write_b128 v142, v[108:111]
	s_waitcnt vmcnt(6)
	ds_write_b128 v143, v[112:115]
	s_waitcnt vmcnt(5)
	ds_write_b128 v144, v[116:119]
	s_waitcnt vmcnt(4)
	ds_write_b128 v145, v[120:123]
	s_waitcnt vmcnt(3)
	ds_write_b128 v146, v[124:127]
	s_waitcnt vmcnt(2)
	ds_write_b128 v147, v[128:131]
	s_waitcnt vmcnt(1)
	ds_write_b128 v148, v[132:135]
	s_waitcnt vmcnt(0)
	ds_write_b128 v149, v[136:139]

.LBB0_913:
	v_mov_b32_e32 v87, v206
	s_movk_i32 s0, 0x27ff
	s_waitcnt lgkmcnt(0)
	s_barrier
	s_nop 0
	v_cmp_lt_i32_e32 vcc, s0, v87
	v_lshlrev_b32_e32 v4, 2, v87
	s_and_saveexec_b64 s[0:1], vcc
	s_xor_b64 s[0:1], exec, s[0:1]
	v_lshlrev_b32_e32 v4, 2, v87
	s_andn2_saveexec_b64 s[4:5], s[0:1]
	s_cbranch_execz .LBB0_923
	s_mov_b64 s[6:7], 0
	v_readlane_b32 s36, v252, 17
	v_readlane_b32 s37, v252, 18
	v_readlane_b32 s38, v252, 19
	v_readlane_b32 s39, v252, 20
	v_readlane_b32 s40, v252, 21
	v_readlane_b32 s41, v252, 22
	v_readlane_b32 s42, v252, 23
	v_readlane_b32 s43, v252, 24
	v_readlane_b32 s44, v252, 25
	v_readlane_b32 s45, v252, 26
	v_readlane_b32 s46, v252, 27
	v_readlane_b32 s47, v252, 28
	v_readlane_b32 s48, v252, 29
	v_readlane_b32 s49, v252, 30
	v_readlane_b32 s50, v252, 31
	v_readlane_b32 s51, v252, 32
	v_add_u32_e32 v160, 0x1000, v4
	v_add_u32_e32 v161, 0x2000, v4
	v_add_u32_e32 v162, 0x3000, v4
	v_add_u32_e32 v163, 0x4000, v4
	v_add_u32_e32 v164, 0x5000, v4
	v_add_u32_e32 v165, 0x6000, v4
	v_add_u32_e32 v166, 0x7000, v4
	global_load_dword v140, v4, s[38:39]
	global_load_dword v141, v4, s[38:39] offset:2048
	global_load_dword v142, v160, s[38:39]
	global_load_dword v143, v160, s[38:39] offset:2048
	global_load_dword v144, v4, s[36:37]
	global_load_dword v145, v4, s[36:37] offset:2048
	global_load_dword v146, v160, s[36:37]
	global_load_dword v147, v160, s[36:37] offset:2048
	global_load_dword v148, v161, s[36:37]
	global_load_dword v149, v161, s[36:37] offset:2048
	global_load_dword v150, v162, s[36:37]
	global_load_dword v151, v162, s[36:37] offset:2048
	global_load_dword v152, v163, s[36:37]
	global_load_dword v153, v163, s[36:37] offset:2048
	global_load_dword v154, v164, s[36:37]
	global_load_dword v155, v164, s[36:37] offset:2048
	global_load_dword v156, v165, s[36:37]
	global_load_dword v157, v165, s[36:37] offset:2048
	global_load_dword v158, v166, s[36:37]
	global_load_dword v159, v166, s[36:37] offset:2048
	s_waitcnt vmcnt(19)
	v_mul_f32_e32 v2, 0xbfb8aa3b, v140
	v_exp_f32_e32 v2, v2
	s_nop 0
	v_add_f32_e32 v2, 1.0, v2
	v_div_scale_f32 v3, s[0:1], v2, v2, v140
	v_rcp_f32_e32 v7, v3
	s_nop 0
	v_fma_f32 v8, -v3, v7, 1.0
	v_fmac_f32_e32 v7, v8, v7
	v_div_scale_f32 v8, vcc, v140, v2, v140
	v_mul_f32_e32 v9, v8, v7
	v_fma_f32 v10, -v3, v9, v8
	v_fmac_f32_e32 v9, v10, v7
	v_fma_f32 v3, -v3, v9, v8
	v_div_fmas_f32 v3, v3, v7, v9
	v_div_fixup_f32 v0, v3, v2, v140
	ds_write_b32 v4, v0
	s_waitcnt vmcnt(18)
	v_mul_f32_e32 v2, 0xbfb8aa3b, v141
	v_exp_f32_e32 v2, v2
	s_nop 0
	v_add_f32_e32 v2, 1.0, v2
	v_div_scale_f32 v3, s[0:1], v2, v2, v141
	v_rcp_f32_e32 v7, v3
	s_nop 0
	v_fma_f32 v8, -v3, v7, 1.0
	v_fmac_f32_e32 v7, v8, v7
	v_div_scale_f32 v8, vcc, v141, v2, v141
	v_mul_f32_e32 v9, v8, v7
	v_fma_f32 v10, -v3, v9, v8
	v_fmac_f32_e32 v9, v10, v7
	v_fma_f32 v3, -v3, v9, v8
	v_div_fmas_f32 v3, v3, v7, v9
	v_div_fixup_f32 v0, v3, v2, v141
	ds_write_b32 v4, v0 offset:2048
	s_waitcnt vmcnt(17)
	v_mul_f32_e32 v2, 0xbfb8aa3b, v142
	v_exp_f32_e32 v2, v2
	s_nop 0
	v_add_f32_e32 v2, 1.0, v2
	v_div_scale_f32 v3, s[0:1], v2, v2, v142
	v_rcp_f32_e32 v7, v3
	s_nop 0
	v_fma_f32 v8, -v3, v7, 1.0
	v_fmac_f32_e32 v7, v8, v7
	v_div_scale_f32 v8, vcc, v142, v2, v142
	v_mul_f32_e32 v9, v8, v7
	v_fma_f32 v10, -v3, v9, v8
	v_fmac_f32_e32 v9, v10, v7
	v_fma_f32 v3, -v3, v9, v8
	v_div_fmas_f32 v3, v3, v7, v9
	v_div_fixup_f32 v0, v3, v2, v142
	ds_write_b32 v4, v0 offset:4096
	s_waitcnt vmcnt(16)
	v_mul_f32_e32 v2, 0xbfb8aa3b, v143
	v_exp_f32_e32 v2, v2
	s_nop 0
	v_add_f32_e32 v2, 1.0, v2
	v_div_scale_f32 v3, s[0:1], v2, v2, v143
	v_rcp_f32_e32 v7, v3
	s_nop 0
	v_fma_f32 v8, -v3, v7, 1.0
	v_fmac_f32_e32 v7, v8, v7
	v_div_scale_f32 v8, vcc, v143, v2, v143
	v_mul_f32_e32 v9, v8, v7
	v_fma_f32 v10, -v3, v9, v8
	v_fmac_f32_e32 v9, v10, v7
	v_fma_f32 v3, -v3, v9, v8
	v_div_fmas_f32 v3, v3, v7, v9
	v_div_fixup_f32 v0, v3, v2, v143
	ds_write_b32 v4, v0 offset:6144
	s_waitcnt vmcnt(15)
	v_mul_f32_e32 v2, 0xbfb8aa3b, v144
	v_exp_f32_e32 v2, v2
	s_nop 0
	v_add_f32_e32 v2, 1.0, v2
	v_div_scale_f32 v3, s[0:1], v2, v2, v144
	v_rcp_f32_e32 v7, v3
	s_nop 0
	v_fma_f32 v8, -v3, v7, 1.0
	v_fmac_f32_e32 v7, v8, v7
	v_div_scale_f32 v8, vcc, v144, v2, v144
	v_mul_f32_e32 v9, v8, v7
	v_fma_f32 v10, -v3, v9, v8
	v_fmac_f32_e32 v9, v10, v7
	v_fma_f32 v3, -v3, v9, v8
	v_div_fmas_f32 v3, v3, v7, v9
	v_div_fixup_f32 v0, v3, v2, v144
	ds_write_b32 v4, v0 offset:8192
	s_waitcnt vmcnt(14)
	v_mul_f32_e32 v2, 0xbfb8aa3b, v145
	v_exp_f32_e32 v2, v2
	s_nop 0
	v_add_f32_e32 v2, 1.0, v2
	v_div_scale_f32 v3, s[0:1], v2, v2, v145
	v_rcp_f32_e32 v7, v3
	s_nop 0
	v_fma_f32 v8, -v3, v7, 1.0
	v_fmac_f32_e32 v7, v8, v7
	v_div_scale_f32 v8, vcc, v145, v2, v145
	v_mul_f32_e32 v9, v8, v7
	v_fma_f32 v10, -v3, v9, v8
	v_fmac_f32_e32 v9, v10, v7
	v_fma_f32 v3, -v3, v9, v8
	v_div_fmas_f32 v3, v3, v7, v9
	v_div_fixup_f32 v0, v3, v2, v145
	ds_write_b32 v4, v0 offset:10240
	s_waitcnt vmcnt(13)
	v_mul_f32_e32 v2, 0xbfb8aa3b, v146
	v_exp_f32_e32 v2, v2
	s_nop 0
	v_add_f32_e32 v2, 1.0, v2
	v_div_scale_f32 v3, s[0:1], v2, v2, v146
	v_rcp_f32_e32 v7, v3
	s_nop 0
	v_fma_f32 v8, -v3, v7, 1.0
	v_fmac_f32_e32 v7, v8, v7
	v_div_scale_f32 v8, vcc, v146, v2, v146
	v_mul_f32_e32 v9, v8, v7
	v_fma_f32 v10, -v3, v9, v8
	v_fmac_f32_e32 v9, v10, v7
	v_fma_f32 v3, -v3, v9, v8
	v_div_fmas_f32 v3, v3, v7, v9
	v_div_fixup_f32 v0, v3, v2, v146
	ds_write_b32 v4, v0 offset:12288
	s_waitcnt vmcnt(12)
	v_mul_f32_e32 v2, 0xbfb8aa3b, v147
	v_exp_f32_e32 v2, v2
	s_nop 0
	v_add_f32_e32 v2, 1.0, v2
	v_div_scale_f32 v3, s[0:1], v2, v2, v147
	v_rcp_f32_e32 v7, v3
	s_nop 0
	v_fma_f32 v8, -v3, v7, 1.0
	v_fmac_f32_e32 v7, v8, v7
	v_div_scale_f32 v8, vcc, v147, v2, v147
	v_mul_f32_e32 v9, v8, v7
	v_fma_f32 v10, -v3, v9, v8
	v_fmac_f32_e32 v9, v10, v7
	v_fma_f32 v3, -v3, v9, v8
	v_div_fmas_f32 v3, v3, v7, v9
	v_div_fixup_f32 v0, v3, v2, v147
	ds_write_b32 v4, v0 offset:14336
	s_waitcnt vmcnt(11)
	v_mul_f32_e32 v2, 0xbfb8aa3b, v148
	v_exp_f32_e32 v2, v2
	s_nop 0
	v_add_f32_e32 v2, 1.0, v2
	v_div_scale_f32 v3, s[0:1], v2, v2, v148
	v_rcp_f32_e32 v7, v3
	s_nop 0
	v_fma_f32 v8, -v3, v7, 1.0
	v_fmac_f32_e32 v7, v8, v7
	v_div_scale_f32 v8, vcc, v148, v2, v148
	v_mul_f32_e32 v9, v8, v7
	v_fma_f32 v10, -v3, v9, v8
	v_fmac_f32_e32 v9, v10, v7
	v_fma_f32 v3, -v3, v9, v8
	v_div_fmas_f32 v3, v3, v7, v9
	v_div_fixup_f32 v0, v3, v2, v148
	ds_write_b32 v4, v0 offset:16384
	s_waitcnt vmcnt(10)
	v_mul_f32_e32 v2, 0xbfb8aa3b, v149
	v_exp_f32_e32 v2, v2
	s_nop 0
	v_add_f32_e32 v2, 1.0, v2
	v_div_scale_f32 v3, s[0:1], v2, v2, v149
	v_rcp_f32_e32 v7, v3
	s_nop 0
	v_fma_f32 v8, -v3, v7, 1.0
	v_fmac_f32_e32 v7, v8, v7
	v_div_scale_f32 v8, vcc, v149, v2, v149
	v_mul_f32_e32 v9, v8, v7
	v_fma_f32 v10, -v3, v9, v8
	v_fmac_f32_e32 v9, v10, v7
	v_fma_f32 v3, -v3, v9, v8
	v_div_fmas_f32 v3, v3, v7, v9
	v_div_fixup_f32 v0, v3, v2, v149
	ds_write_b32 v4, v0 offset:18432
	s_waitcnt vmcnt(9)
	v_mul_f32_e32 v2, 0xbfb8aa3b, v150
	v_exp_f32_e32 v2, v2
	s_nop 0
	v_add_f32_e32 v2, 1.0, v2
	v_div_scale_f32 v3, s[0:1], v2, v2, v150
	v_rcp_f32_e32 v7, v3
	s_nop 0
	v_fma_f32 v8, -v3, v7, 1.0
	v_fmac_f32_e32 v7, v8, v7
	v_div_scale_f32 v8, vcc, v150, v2, v150
	v_mul_f32_e32 v9, v8, v7
	v_fma_f32 v10, -v3, v9, v8
	v_fmac_f32_e32 v9, v10, v7
	v_fma_f32 v3, -v3, v9, v8
	v_div_fmas_f32 v3, v3, v7, v9
	v_div_fixup_f32 v0, v3, v2, v150
	ds_write_b32 v4, v0 offset:20480
	s_waitcnt vmcnt(8)
	v_mul_f32_e32 v2, 0xbfb8aa3b, v151
	v_exp_f32_e32 v2, v2
	s_nop 0
	v_add_f32_e32 v2, 1.0, v2
	v_div_scale_f32 v3, s[0:1], v2, v2, v151
	v_rcp_f32_e32 v7, v3
	s_nop 0
	v_fma_f32 v8, -v3, v7, 1.0
	v_fmac_f32_e32 v7, v8, v7
	v_div_scale_f32 v8, vcc, v151, v2, v151
	v_mul_f32_e32 v9, v8, v7
	v_fma_f32 v10, -v3, v9, v8
	v_fmac_f32_e32 v9, v10, v7
	v_fma_f32 v3, -v3, v9, v8
	v_div_fmas_f32 v3, v3, v7, v9
	v_div_fixup_f32 v0, v3, v2, v151
	ds_write_b32 v4, v0 offset:22528
	s_waitcnt vmcnt(7)
	v_mul_f32_e32 v2, 0xbfb8aa3b, v152
	v_exp_f32_e32 v2, v2
	s_nop 0
	v_add_f32_e32 v2, 1.0, v2
	v_div_scale_f32 v3, s[0:1], v2, v2, v152
	v_rcp_f32_e32 v7, v3
	s_nop 0
	v_fma_f32 v8, -v3, v7, 1.0
	v_fmac_f32_e32 v7, v8, v7
	v_div_scale_f32 v8, vcc, v152, v2, v152
	v_mul_f32_e32 v9, v8, v7
	v_fma_f32 v10, -v3, v9, v8
	v_fmac_f32_e32 v9, v10, v7
	v_fma_f32 v3, -v3, v9, v8
	v_div_fmas_f32 v3, v3, v7, v9
	v_div_fixup_f32 v0, v3, v2, v152
	ds_write_b32 v4, v0 offset:24576
	s_waitcnt vmcnt(6)
	v_mul_f32_e32 v2, 0xbfb8aa3b, v153
	v_exp_f32_e32 v2, v2
	s_nop 0
	v_add_f32_e32 v2, 1.0, v2
	v_div_scale_f32 v3, s[0:1], v2, v2, v153
	v_rcp_f32_e32 v7, v3
	s_nop 0
	v_fma_f32 v8, -v3, v7, 1.0
	v_fmac_f32_e32 v7, v8, v7
	v_div_scale_f32 v8, vcc, v153, v2, v153
	v_mul_f32_e32 v9, v8, v7
	v_fma_f32 v10, -v3, v9, v8
	v_fmac_f32_e32 v9, v10, v7
	v_fma_f32 v3, -v3, v9, v8
	v_div_fmas_f32 v3, v3, v7, v9
	v_div_fixup_f32 v0, v3, v2, v153
	ds_write_b32 v4, v0 offset:26624
	s_waitcnt vmcnt(5)
	v_mul_f32_e32 v2, 0xbfb8aa3b, v154
	v_exp_f32_e32 v2, v2
	s_nop 0
	v_add_f32_e32 v2, 1.0, v2
	v_div_scale_f32 v3, s[0:1], v2, v2, v154
	v_rcp_f32_e32 v7, v3
	s_nop 0
	v_fma_f32 v8, -v3, v7, 1.0
	v_fmac_f32_e32 v7, v8, v7
	v_div_scale_f32 v8, vcc, v154, v2, v154
	v_mul_f32_e32 v9, v8, v7
	v_fma_f32 v10, -v3, v9, v8
	v_fmac_f32_e32 v9, v10, v7
	v_fma_f32 v3, -v3, v9, v8
	v_div_fmas_f32 v3, v3, v7, v9
	v_div_fixup_f32 v0, v3, v2, v154
	ds_write_b32 v4, v0 offset:28672
	s_waitcnt vmcnt(4)
	v_mul_f32_e32 v2, 0xbfb8aa3b, v155
	v_exp_f32_e32 v2, v2
	s_nop 0
	v_add_f32_e32 v2, 1.0, v2
	v_div_scale_f32 v3, s[0:1], v2, v2, v155
	v_rcp_f32_e32 v7, v3
	s_nop 0
	v_fma_f32 v8, -v3, v7, 1.0
	v_fmac_f32_e32 v7, v8, v7
	v_div_scale_f32 v8, vcc, v155, v2, v155
	v_mul_f32_e32 v9, v8, v7
	v_fma_f32 v10, -v3, v9, v8
	v_fmac_f32_e32 v9, v10, v7
	v_fma_f32 v3, -v3, v9, v8
	v_div_fmas_f32 v3, v3, v7, v9
	v_div_fixup_f32 v0, v3, v2, v155
	ds_write_b32 v4, v0 offset:30720
	s_waitcnt vmcnt(3)
	v_mul_f32_e32 v2, 0xbfb8aa3b, v156
	v_exp_f32_e32 v2, v2
	s_nop 0
	v_add_f32_e32 v2, 1.0, v2
	v_div_scale_f32 v3, s[0:1], v2, v2, v156
	v_rcp_f32_e32 v7, v3
	s_nop 0
	v_fma_f32 v8, -v3, v7, 1.0
	v_fmac_f32_e32 v7, v8, v7
	v_div_scale_f32 v8, vcc, v156, v2, v156
	v_mul_f32_e32 v9, v8, v7
	v_fma_f32 v10, -v3, v9, v8
	v_fmac_f32_e32 v9, v10, v7
	v_fma_f32 v3, -v3, v9, v8
	v_div_fmas_f32 v3, v3, v7, v9
	v_div_fixup_f32 v0, v3, v2, v156
	ds_write_b32 v4, v0 offset:32768
	s_waitcnt vmcnt(2)
	v_mul_f32_e32 v2, 0xbfb8aa3b, v157
	v_exp_f32_e32 v2, v2
	s_nop 0
	v_add_f32_e32 v2, 1.0, v2
	v_div_scale_f32 v3, s[0:1], v2, v2, v157
	v_rcp_f32_e32 v7, v3
	s_nop 0
	v_fma_f32 v8, -v3, v7, 1.0
	v_fmac_f32_e32 v7, v8, v7
	v_div_scale_f32 v8, vcc, v157, v2, v157
	v_mul_f32_e32 v9, v8, v7
	v_fma_f32 v10, -v3, v9, v8
	v_fmac_f32_e32 v9, v10, v7
	v_fma_f32 v3, -v3, v9, v8
	v_div_fmas_f32 v3, v3, v7, v9
	v_div_fixup_f32 v0, v3, v2, v157
	ds_write_b32 v4, v0 offset:34816
	s_waitcnt vmcnt(1)
	v_mul_f32_e32 v2, 0xbfb8aa3b, v158
	v_exp_f32_e32 v2, v2
	s_nop 0
	v_add_f32_e32 v2, 1.0, v2
	v_div_scale_f32 v3, s[0:1], v2, v2, v158
	v_rcp_f32_e32 v7, v3
	s_nop 0
	v_fma_f32 v8, -v3, v7, 1.0
	v_fmac_f32_e32 v7, v8, v7
	v_div_scale_f32 v8, vcc, v158, v2, v158
	v_mul_f32_e32 v9, v8, v7
	v_fma_f32 v10, -v3, v9, v8
	v_fmac_f32_e32 v9, v10, v7
	v_fma_f32 v3, -v3, v9, v8
	v_div_fmas_f32 v3, v3, v7, v9
	v_div_fixup_f32 v0, v3, v2, v158
	ds_write_b32 v4, v0 offset:36864
	s_waitcnt vmcnt(0)
	v_mul_f32_e32 v2, 0xbfb8aa3b, v159
	v_exp_f32_e32 v2, v2
	s_nop 0
	v_add_f32_e32 v2, 1.0, v2
	v_div_scale_f32 v3, s[0:1], v2, v2, v159
	v_rcp_f32_e32 v7, v3
	s_nop 0
	v_fma_f32 v8, -v3, v7, 1.0
	v_fmac_f32_e32 v7, v8, v7
	v_div_scale_f32 v8, vcc, v159, v2, v159
	v_mul_f32_e32 v9, v8, v7
	v_fma_f32 v10, -v3, v9, v8
	v_fmac_f32_e32 v9, v10, v7
	v_fma_f32 v3, -v3, v9, v8
	v_div_fmas_f32 v3, v3, v7, v9
	v_div_fixup_f32 v0, v3, v2, v159
	ds_write_b32 v4, v0 offset:38912
	v_add_u32_e32 v5, 0xa000, v4
	v_add_u32_e32 v6, 0x2800, v87
